# v21 = v18 + FFT long-conv: both workgroup barriers (per-sequence loop top and output stage) moved below the global-load batches so the loads issue before the wave synchronises
# speedup vs baseline: 1.0002x; 1.0002x over previous
.LBB0_683:
	s_or_b64 exec, exec, s[48:49]
	s_lshl_b64 s[2:3], s[42:43], 2
	s_add_u32 s2, s19, s2
	s_addc_u32 s3, s34, s3
	s_lshl_b64 s[20:21], s[46:47], 1
	s_add_u32 s48, s54, s20
	s_addc_u32 s49, s55, s21
	s_add_u32 s46, s48, 0x4000
	s_addc_u32 s47, s49, 0
	v_lshlrev_b64 v[2:3], 1, v[38:39]
	v_lshlrev_b64 v[38:39], 1, v[40:41]
	v_lshl_add_u64 v[6:7], s[48:49], 0, v[2:3]
	v_lshl_add_u64 v[4:5], s[46:47], 0, v[2:3]
	v_lshl_add_u64 v[0:1], s[46:47], 0, v[38:39]
	v_lshlrev_b64 v[40:41], 1, v[36:37]
	global_load_ushort v88, v[6:7], off
	global_load_ushort v89, v[4:5], off
	global_load_ushort v90, v[6:7], off offset:1024
	global_load_ushort v91, v[0:1], off
	global_load_ushort v92, v[6:7], off offset:2048
	v_lshl_add_u64 v[0:1], s[46:47], 0, v[40:41]
	v_lshlrev_b64 v[34:35], 1, v[34:35]
	global_load_ushort v37, v[0:1], off
	global_load_ushort v93, v[6:7], off offset:3072
	v_lshl_add_u64 v[0:1], s[46:47], 0, v[34:35]
	v_lshlrev_b64 v[32:33], 1, v[32:33]
	global_load_ushort v94, v[0:1], off
	v_lshl_add_u64 v[0:1], s[48:49], 0, v[32:33]
	global_load_ushort v95, v[0:1], off
	v_lshl_add_u64 v[0:1], s[46:47], 0, v[32:33]
	v_lshlrev_b64 v[30:31], 1, v[30:31]
	global_load_ushort v96, v[0:1], off
	v_lshl_add_u64 v[0:1], s[48:49], 0, v[30:31]
	global_load_ushort v97, v[0:1], off
	v_lshl_add_u64 v[0:1], s[46:47], 0, v[30:31]
	v_lshlrev_b64 v[28:29], 1, v[28:29]
	global_load_ushort v98, v[0:1], off
	v_lshl_add_u64 v[0:1], s[48:49], 0, v[28:29]
	global_load_ushort v99, v[0:1], off
	v_lshl_add_u64 v[0:1], s[46:47], 0, v[28:29]
	v_lshlrev_b64 v[26:27], 1, v[26:27]
	global_load_ushort v100, v[0:1], off
	v_lshl_add_u64 v[0:1], s[48:49], 0, v[26:27]
	global_load_ushort v101, v[0:1], off
	v_lshl_add_u64 v[0:1], s[46:47], 0, v[26:27]
	global_load_dword v74, v[74:75], off
	s_nop 0
	global_load_dword v72, v[72:73], off
	s_nop 0
	global_load_dword v70, v[70:71], off
	s_nop 0
	global_load_dword v68, v[68:69], off
	s_nop 0
	global_load_dword v66, v[66:67], off
	s_nop 0
	global_load_dword v64, v[64:65], off
	s_nop 0
	global_load_dword v62, v[62:63], off
	s_nop 0
	global_load_dword v60, v[60:61], off
	s_nop 0
	global_load_dword v58, v[58:59], off
	s_nop 0
	global_load_dword v56, v[56:57], off
	s_nop 0
	global_load_dword v54, v[54:55], off
	s_nop 0
	global_load_dword v52, v[52:53], off
	s_nop 0
	global_load_dword v50, v[50:51], off
	s_nop 0
	global_load_dword v51, v[46:47], off offset:2048
	s_nop 0
	global_load_dword v48, v[48:49], off
	s_nop 0
	global_load_dword v49, v[46:47], off
	global_load_ushort v53, v[0:1], off
	global_load_dword v36, v195, s[2:3]
	s_add_u32 s20, s56, s20
	s_addc_u32 s21, s57, s21
	v_lshl_add_u64 v[0:1], s[20:21], 0, v[2:3]
	s_add_u32 s2, s20, 0x4000
	s_addc_u32 s3, s21, 0
	v_lshl_add_u64 v[2:3], s[2:3], 0, v[2:3]
	v_lshl_add_u64 v[38:39], s[2:3], 0, v[38:39]
	v_lshl_add_u64 v[40:41], s[2:3], 0, v[40:41]
	v_lshl_add_u64 v[34:35], s[2:3], 0, v[34:35]
	v_lshlrev_b64 v[24:25], 1, v[24:25]
	s_movk_i32 s4, 0x2000
	s_movk_i32 s5, 0x3000
	s_add_i32 s42, s42, s18
	s_cmpk_gt_i32 s42, 0x3ff
	s_waitcnt lgkmcnt(0)
	s_barrier
	s_waitcnt vmcnt(2)
	s_waitcnt vmcnt(1)
	ds_read_b64 v[46:47], v185
	v_lshlrev_b32_e32 v55, 16, v88
	v_lshlrev_b32_e32 v57, 16, v89
	v_lshlrev_b32_e32 v37, 16, v37
	s_waitcnt vmcnt(0) lgkmcnt(0)
	v_fma_f32 v46, v36, v49, v46
	v_fmac_f32_e32 v47, v36, v48
	v_mul_f32_e32 v46, v46, v55
	v_mul_f32_e32 v47, v47, v57
	v_cvt_pk_bf16_f32 v46, v46, v46
	global_store_short v[0:1], v46, off
	v_cvt_pk_bf16_f32 v48, v47, v47
	ds_read_b64 v[46:47], v184 offset:4096
	v_lshlrev_b32_e32 v49, 16, v90
	v_lshlrev_b32_e32 v55, 16, v91
	global_store_short v[2:3], v48, off
	s_waitcnt lgkmcnt(0)
	v_fma_f32 v46, v36, v51, v46
	v_fmac_f32_e32 v47, v36, v50
	v_mul_f32_e32 v46, v46, v49
	v_mul_f32_e32 v47, v47, v55
	v_cvt_pk_bf16_f32 v46, v46, v46
	global_store_short v[0:1], v46, off offset:1024
	v_cvt_pk_bf16_f32 v48, v47, v47
	ds_read_b64 v[46:47], v183 offset:8192
	v_lshlrev_b32_e32 v49, 16, v92
	global_store_short v[38:39], v48, off
	s_waitcnt lgkmcnt(0)
	v_fma_f32 v38, v36, v52, v46
	v_fmac_f32_e32 v47, v36, v54
	v_mul_f32_e32 v38, v38, v49
	v_mul_f32_e32 v37, v47, v37
	v_cvt_pk_bf16_f32 v38, v38, v38
	global_store_short v[0:1], v38, off offset:2048
	v_cvt_pk_bf16_f32 v37, v37, v37
	ds_read_b64 v[38:39], v182 offset:12288
	v_lshlrev_b32_e32 v46, 16, v93
	global_store_short v[40:41], v37, off
	v_lshlrev_b32_e32 v47, 16, v94
	v_lshlrev_b32_e32 v40, 16, v95
	s_waitcnt lgkmcnt(0)
	v_fma_f32 v37, v36, v56, v38
	v_fmac_f32_e32 v39, v36, v58
	v_mul_f32_e32 v37, v37, v46
	v_mul_f32_e32 v38, v39, v47
	v_cvt_pk_bf16_f32 v37, v37, v37
	global_store_short v[0:1], v37, off offset:3072
	v_cvt_pk_bf16_f32 v37, v38, v38
	ds_read_b64 v[38:39], v181 offset:16384
	global_store_short v[34:35], v37, off
	v_lshlrev_b32_e32 v41, 16, v96
	s_waitcnt lgkmcnt(0)
	v_fma_f32 v34, v36, v60, v38
	v_fmac_f32_e32 v39, v36, v62
	v_mul_f32_e32 v34, v34, v40
	v_mul_f32_e32 v37, v39, v41
	v_cvt_pk_bf16_f32 v38, v34, v34
	v_lshl_add_u64 v[34:35], s[20:21], 0, v[32:33]
	global_store_short v[34:35], v38, off
	v_cvt_pk_bf16_f32 v37, v37, v37
	ds_read_b64 v[34:35], v180 offset:20480
	v_lshl_add_u64 v[32:33], s[2:3], 0, v[32:33]
	global_store_short v[32:33], v37, off
	v_lshlrev_b32_e32 v32, 16, v97
	s_waitcnt lgkmcnt(0)
	v_fma_f32 v33, v36, v64, v34
	v_mul_f32_e32 v32, v33, v32
	v_lshlrev_b32_e32 v33, 16, v98
	v_fmac_f32_e32 v35, v36, v66
	v_mul_f32_e32 v34, v35, v33
	v_cvt_pk_bf16_f32 v35, v32, v32
	v_lshl_add_u64 v[32:33], s[20:21], 0, v[30:31]
	global_store_short v[32:33], v35, off
	v_cvt_pk_bf16_f32 v34, v34, v34
	ds_read_b64 v[32:33], v179 offset:24576
	v_lshl_add_u64 v[30:31], s[2:3], 0, v[30:31]
	global_store_short v[30:31], v34, off
	v_lshlrev_b32_e32 v30, 16, v99
	s_waitcnt lgkmcnt(0)
	v_fma_f32 v31, v36, v68, v32
	v_mul_f32_e32 v30, v31, v30
	v_lshlrev_b32_e32 v31, 16, v100
	v_fmac_f32_e32 v33, v36, v70
	v_mul_f32_e32 v32, v33, v31
	v_cvt_pk_bf16_f32 v33, v30, v30
	v_lshl_add_u64 v[30:31], s[20:21], 0, v[28:29]
	global_store_short v[30:31], v33, off
	v_cvt_pk_bf16_f32 v32, v32, v32
	ds_read_b64 v[30:31], v178 offset:28672
	v_lshl_add_u64 v[28:29], s[2:3], 0, v[28:29]
	global_store_short v[28:29], v32, off
	v_lshlrev_b32_e32 v28, 16, v101
	s_waitcnt lgkmcnt(0)
	v_fma_f32 v29, v36, v72, v30
	v_mul_f32_e32 v28, v29, v28
	v_lshlrev_b32_e32 v29, 16, v53
	v_fmac_f32_e32 v31, v36, v74
	v_mul_f32_e32 v30, v31, v29
	v_cvt_pk_bf16_f32 v31, v28, v28
	v_lshl_add_u64 v[28:29], s[20:21], 0, v[26:27]
	v_lshl_add_u64 v[26:27], s[2:3], 0, v[26:27]
	global_store_short v[28:29], v31, off
	v_cvt_pk_bf16_f32 v28, v30, v30
	global_store_short v[26:27], v28, off
	v_lshl_add_u64 v[26:27], s[48:49], 0, v[24:25]
	global_load_ushort v30, v[26:27], off
	v_lshl_add_u64 v[26:27], s[46:47], 0, v[24:25]
	global_load_ushort v31, v[26:27], off
	v_add_co_u32_e32 v26, vcc, s4, v6
	s_nop 1
	v_addc_co_u32_e32 v27, vcc, 0, v7, vcc
	v_add_co_u32_e32 v28, vcc, s4, v4
	global_load_ushort v32, v[26:27], off offset:1024
	s_nop 0
	v_addc_co_u32_e32 v29, vcc, 0, v5, vcc
	v_add_co_u32_e32 v6, vcc, s5, v6
	global_load_ushort v33, v[28:29], off offset:1024
	global_load_ushort v34, v[26:27], off offset:2048
	global_load_ushort v35, v[28:29], off offset:2048
	s_nop 0
	global_load_ushort v26, v[26:27], off offset:3072
	s_nop 0
	global_load_ushort v27, v[28:29], off offset:3072
	v_addc_co_u32_e32 v7, vcc, 0, v7, vcc
	v_add_co_u32_e32 v4, vcc, s5, v4
	global_load_ushort v28, v[6:7], off
	s_nop 0
	v_addc_co_u32_e32 v5, vcc, 0, v5, vcc
	global_load_ushort v29, v[4:5], off
	global_load_ushort v37, v[6:7], off offset:1024
	global_load_ushort v38, v[4:5], off offset:1024
	global_load_ushort v39, v[6:7], off offset:2048
	global_load_ushort v40, v[4:5], off offset:2048
	global_load_ushort v41, v[6:7], off offset:3072
	global_load_dword v46, v[86:87], off
	global_load_dword v47, v[84:85], off
	global_load_dword v48, v[82:83], off
	global_load_dword v49, v[80:81], off
	global_load_dword v50, v[78:79], off
	global_load_dword v51, v[76:77], off
	s_nop 0
	global_load_dword v22, v[22:23], off
	s_nop 0
	global_load_dword v20, v[20:21], off
	s_nop 0
	global_load_dword v18, v[18:19], off
	s_nop 0
	global_load_dword v16, v[16:17], off
	s_nop 0
	global_load_dword v14, v[14:15], off
	s_nop 0
	global_load_dword v12, v[12:13], off
	s_nop 0
	global_load_dword v13, v[10:11], off
	global_load_dword v15, v[8:9], off
	s_nop 0
	global_load_dword v9, v[44:45], off
	global_load_dword v17, v[42:43], off
	global_load_ushort v19, v[4:5], off offset:3072
	s_waitcnt vmcnt(1)
	s_waitcnt vmcnt(0)
	ds_read_b64 v[6:7], v177 offset:32768
	v_lshlrev_b32_e32 v21, 16, v30
	v_lshl_add_u64 v[4:5], s[20:21], 0, v[24:25]
	v_lshlrev_b32_e32 v23, 16, v31
	v_add_co_u32_e32 v8, vcc, s4, v0
	s_waitcnt lgkmcnt(0)
	v_fma_f32 v6, v36, v17, v6
	v_mul_f32_e32 v6, v6, v21
	v_fmac_f32_e32 v7, v36, v9
	v_cvt_pk_bf16_f32 v6, v6, v6
	v_mul_f32_e32 v7, v7, v23
	global_store_short v[4:5], v6, off
	v_cvt_pk_bf16_f32 v6, v7, v7
	ds_read_b64 v[4:5], v176 offset:36864
	v_lshlrev_b32_e32 v7, 16, v32
	v_lshl_add_u64 v[10:11], s[2:3], 0, v[24:25]
	v_addc_co_u32_e32 v9, vcc, 0, v1, vcc
	s_waitcnt lgkmcnt(0)
	v_fma_f32 v4, v36, v15, v4
	v_lshlrev_b32_e32 v17, 16, v33
	v_fmac_f32_e32 v5, v36, v13
	v_mul_f32_e32 v4, v4, v7
	global_store_short v[10:11], v6, off
	v_mul_f32_e32 v5, v5, v17
	v_cvt_pk_bf16_f32 v4, v4, v4
	global_store_short v[8:9], v4, off offset:1024
	v_cvt_pk_bf16_f32 v10, v5, v5
	ds_read_b64 v[6:7], v175 offset:40960
	v_add_co_u32_e32 v4, vcc, s4, v2
	s_waitcnt lgkmcnt(0)
	v_fma_f32 v6, v36, v12, v6
	v_addc_co_u32_e32 v5, vcc, 0, v3, vcc
	global_store_short v[4:5], v10, off offset:1024
	v_lshlrev_b32_e32 v10, 16, v34
	v_mul_f32_e32 v6, v6, v10
	v_lshlrev_b32_e32 v10, 16, v35
	v_fmac_f32_e32 v7, v36, v14
	v_mul_f32_e32 v7, v7, v10
	v_cvt_pk_bf16_f32 v6, v6, v6
	global_store_short v[8:9], v6, off offset:2048
	v_cvt_pk_bf16_f32 v10, v7, v7
	ds_read_b64 v[6:7], v174 offset:45056
	global_store_short v[4:5], v10, off offset:2048
	v_lshlrev_b32_e32 v10, 16, v26
	v_add_co_u32_e32 v0, vcc, s5, v0
	s_waitcnt lgkmcnt(0)
	v_fma_f32 v6, v36, v16, v6
	v_mul_f32_e32 v6, v6, v10
	v_lshlrev_b32_e32 v10, 16, v27
	v_fmac_f32_e32 v7, v36, v18
	v_mul_f32_e32 v7, v7, v10
	v_cvt_pk_bf16_f32 v6, v6, v6
	global_store_short v[8:9], v6, off offset:3072
	v_cvt_pk_bf16_f32 v8, v7, v7
	ds_read_b64 v[6:7], v173 offset:49152
	global_store_short v[4:5], v8, off offset:3072
	v_lshlrev_b32_e32 v4, 16, v28
	v_addc_co_u32_e32 v1, vcc, 0, v1, vcc
	s_waitcnt lgkmcnt(0)
	v_fma_f32 v5, v36, v20, v6
	v_mul_f32_e32 v4, v5, v4
	v_lshlrev_b32_e32 v5, 16, v29
	v_fmac_f32_e32 v7, v36, v22
	v_mul_f32_e32 v5, v7, v5
	v_cvt_pk_bf16_f32 v4, v4, v4
	global_store_short v[0:1], v4, off
	v_cvt_pk_bf16_f32 v6, v5, v5
	ds_read_b64 v[4:5], v172 offset:53248
	v_add_co_u32_e32 v2, vcc, s5, v2
	s_waitcnt lgkmcnt(0)
	v_fma_f32 v4, v36, v51, v4
	v_addc_co_u32_e32 v3, vcc, 0, v3, vcc
	global_store_short v[2:3], v6, off
	v_lshlrev_b32_e32 v6, 16, v37
	v_mul_f32_e32 v4, v4, v6
	v_lshlrev_b32_e32 v6, 16, v38
	v_fmac_f32_e32 v5, v36, v50
	v_mul_f32_e32 v5, v5, v6
	v_cvt_pk_bf16_f32 v4, v4, v4
	global_store_short v[0:1], v4, off offset:1024
	v_cvt_pk_bf16_f32 v6, v5, v5
	ds_read_b64 v[4:5], v171 offset:57344
	global_store_short v[2:3], v6, off offset:1024
	v_lshlrev_b32_e32 v6, 16, v39
	s_waitcnt lgkmcnt(0)
	v_fma_f32 v4, v36, v49, v4
	v_mul_f32_e32 v4, v4, v6
	v_lshlrev_b32_e32 v6, 16, v40
	v_fmac_f32_e32 v5, v36, v48
	v_mul_f32_e32 v5, v5, v6
	v_cvt_pk_bf16_f32 v4, v4, v4
	global_store_short v[0:1], v4, off offset:2048
	v_cvt_pk_bf16_f32 v6, v5, v5
	ds_read_b64 v[4:5], v170 offset:61440
	global_store_short v[2:3], v6, off offset:2048
	v_lshlrev_b32_e32 v6, 16, v41
	s_waitcnt lgkmcnt(0)
	v_fma_f32 v4, v36, v47, v4
	v_mul_f32_e32 v4, v4, v6
	v_lshlrev_b32_e32 v6, 16, v19
	v_fmac_f32_e32 v5, v36, v46
	v_mul_f32_e32 v5, v5, v6
	v_cvt_pk_bf16_f32 v4, v4, v4
	global_store_short v[0:1], v4, off offset:3072
	v_cvt_pk_bf16_f32 v0, v5, v5
	global_store_short v[2:3], v0, off offset:3072
	s_cbranch_scc1 .LBB0_722
.LBB0_684:
	s_ashr_i32 s43, s42, 31
	v_mov_b32_e32 v38, v168
	s_lshl_b64 s[46:47], s[42:43], 16
	s_add_u32 s2, s44, s46
	v_add_u32_e32 v36, 0x400, v38
	v_add_u32_e32 v34, 0x600, v38
	v_add_u32_e32 v32, 0x800, v38
	v_add_u32_e32 v30, 0xa00, v38
	v_add_u32_e32 v28, 0xc00, v38
	v_add_u32_e32 v26, 0xe00, v38
	v_add_u32_e32 v24, 0x1000, v38
	s_addc_u32 s3, s45, s47
	v_ashrrev_i32_e32 v39, 31, v38
	v_ashrrev_i32_e32 v37, 31, v36
	v_ashrrev_i32_e32 v35, 31, v34
	v_ashrrev_i32_e32 v33, 31, v32
	v_ashrrev_i32_e32 v31, 31, v30
	v_ashrrev_i32_e32 v29, 31, v28
	v_ashrrev_i32_e32 v27, 31, v26
	v_ashrrev_i32_e32 v25, 31, v24
	v_lshl_add_u64 v[16:17], v[38:39], 2, s[2:3]
	v_lshl_add_u64 v[0:1], v[36:37], 2, s[2:3]
	v_lshl_add_u64 v[2:3], v[34:35], 2, s[2:3]
	v_lshl_add_u64 v[4:5], v[32:33], 2, s[2:3]
	v_lshl_add_u64 v[6:7], v[30:31], 2, s[2:3]
	v_lshl_add_u64 v[8:9], v[28:29], 2, s[2:3]
	v_lshl_add_u64 v[10:11], v[26:27], 2, s[2:3]
	v_lshl_add_u64 v[12:13], v[24:25], 2, s[2:3]
	s_movk_i32 s2, 0x7000
	v_add_co_u32_e32 v14, vcc, s2, v16
	s_mov_b32 s2, 0x8000
	s_nop 0
	v_addc_co_u32_e32 v15, vcc, 0, v17, vcc
	v_add_co_u32_e32 v18, vcc, s2, v16
	s_movk_i32 s2, 0x6000
	s_nop 0
	v_addc_co_u32_e32 v19, vcc, 0, v17, vcc
	v_add_co_u32_e32 v20, vcc, s2, v16
	s_mov_b32 s2, 0xf000
	s_nop 0
	v_addc_co_u32_e32 v21, vcc, 0, v17, vcc
	v_add_co_u32_e32 v22, vcc, s0, v16
	global_load_dword v42, v[16:17], off offset:2048
	global_load_dword v44, v[10:11], off
	global_load_dword v46, v[8:9], off
	global_load_dword v48, v[6:7], off
	global_load_dword v50, v[4:5], off
	global_load_dword v52, v[2:3], off
	global_load_dword v54, v[0:1], off
	global_load_dword v194, v[16:17], off
	v_addc_co_u32_e32 v23, vcc, 0, v17, vcc
	v_add_co_u32_e32 v40, vcc, s29, v16
	v_add_u32_e32 v5, 0x1600, v38
	s_nop 0
	v_addc_co_u32_e32 v41, vcc, 0, v17, vcc
	v_add_co_u32_e32 v2, vcc, s2, v16
	s_mov_b32 s2, 0xe000
	s_nop 0
	v_addc_co_u32_e32 v3, vcc, 0, v17, vcc
	v_add_co_u32_e32 v6, vcc, s2, v16
	s_mov_b32 s2, 0xc000
	s_nop 0
	v_addc_co_u32_e32 v7, vcc, 0, v17, vcc
	v_add_co_u32_e32 v10, vcc, s1, v16
	global_load_dword v56, v[14:15], off offset:2048
	global_load_dword v58, v[20:21], off offset:2048
	global_load_dword v60, v[22:23], off offset:2048
	global_load_dword v62, v[40:41], off offset:2048
	global_load_dword v0, v[2:3], off
	s_nop 0
	global_load_dword v22, v[22:23], off
	s_nop 0
	global_load_dword v20, v[20:21], off
	s_nop 0
	global_load_dword v64, v[12:13], off
	v_addc_co_u32_e32 v11, vcc, 0, v17, vcc
	v_add_co_u32_e32 v14, vcc, s2, v16
	s_mov_b32 s2, 0xb000
	s_nop 0
	v_addc_co_u32_e32 v15, vcc, 0, v17, vcc
	v_add_co_u32_e32 v40, vcc, s2, v16
	s_mov_b32 s2, 0xa000
	s_nop 0
	v_addc_co_u32_e32 v41, vcc, 0, v17, vcc
	v_add_co_u32_e32 v68, vcc, s2, v16
	s_mov_b32 s2, 0x9000
	s_nop 0
	v_addc_co_u32_e32 v69, vcc, 0, v17, vcc
	v_add_co_u32_e32 v16, vcc, s2, v16
	global_load_dword v2, v[2:3], off offset:2048
	s_nop 0
	global_load_dword v4, v[6:7], off offset:2048
	global_load_dword v8, v[10:11], off offset:2048
	global_load_dword v12, v[14:15], off offset:2048
	global_load_dword v66, v[40:41], off
	s_nop 0
	global_load_dword v14, v[14:15], off
	s_nop 0
	global_load_dword v10, v[10:11], off
	s_nop 0
	global_load_dword v6, v[6:7], off
	v_addc_co_u32_e32 v17, vcc, 0, v17, vcc
	global_load_dword v70, v[18:19], off offset:-4096
	global_load_dword v72, v[40:41], off offset:2048
	global_load_dword v74, v[68:69], off offset:2048
	global_load_dword v76, v[18:19], off offset:2048
	s_nop 0
	global_load_dword v18, v[18:19], off
	s_nop 0
	global_load_dword v78, v[16:17], off offset:2048
	s_nop 0
	global_load_dword v16, v[16:17], off
	s_nop 0
	global_load_dword v68, v[68:69], off
	v_add_u32_e32 v3, 0x1400, v38
	v_ashrrev_i32_e32 v3, 4, v3
	v_lshlrev_b32_e32 v57, 3, v38
	v_lshlrev_b32_e32 v3, 3, v3
	v_add3_u32 v175, 0, v3, v57
	v_ashrrev_i32_e32 v3, 4, v5
	v_add_u32_e32 v7, 0x1800, v38
	v_lshlrev_b32_e32 v3, 3, v3
	v_add3_u32 v174, 0, v3, v57
	v_ashrrev_i32_e32 v3, 4, v7
	v_add_u32_e32 v9, 0x1a00, v38
	v_lshlrev_b32_e32 v3, 3, v3
	v_add3_u32 v173, 0, v3, v57
	v_ashrrev_i32_e32 v3, 4, v9
	v_add_u32_e32 v11, 0x1c00, v38
	v_lshlrev_b32_e32 v3, 3, v3
	v_ashrrev_i32_e32 v19, 4, v38
	v_add3_u32 v172, 0, v3, v57
	v_ashrrev_i32_e32 v3, 4, v11
	v_add_u32_e32 v13, 0x1e00, v38
	v_lshlrev_b32_e32 v19, 3, v19
	v_lshlrev_b32_e32 v3, 3, v3
	s_waitcnt vmcnt(7)
	v_add3_u32 v185, 0, v19, v57
	v_add_f32_e64 v19, |v194|, |v42|
	v_add3_u32 v171, 0, v3, v57
	v_ashrrev_i32_e32 v3, 4, v13
	v_add_u32_e32 v15, 0x2000, v38
	v_add_f32_e64 v19, |v54|, v19
	v_lshlrev_b32_e32 v3, 3, v3
	v_add_f32_e64 v19, |v52|, v19
	v_add3_u32 v170, 0, v3, v57
	v_ashrrev_i32_e32 v3, 4, v15
	v_add_u32_e32 v17, 0x2200, v38
	v_add_f32_e64 v19, |v50|, v19
	v_lshlrev_b32_e32 v3, 3, v3
	v_lshlrev_b32_e32 v5, 3, v15
	v_add_f32_e64 v19, |v48|, v19
	v_add3_u32 v206, 0, v3, v5
	v_ashrrev_i32_e32 v3, 4, v17
	v_add_u32_e32 v41, 0x2400, v38
	v_add_f32_e64 v19, |v46|, v19
	v_lshlrev_b32_e32 v3, 3, v3
	v_lshlrev_b32_e32 v5, 3, v17
	v_add_u32_e32 v1, 0x1200, v38
	v_add_f32_e64 v19, |v44|, v19
	v_add3_u32 v205, 0, v3, v5
	v_ashrrev_i32_e32 v3, 4, v41
	v_add_u32_e32 v67, 0x2600, v38
	v_add_f32_e64 v19, |v64|, v19
	v_ashrrev_i32_e32 v1, 4, v1
	v_lshlrev_b32_e32 v3, 3, v3
	v_lshlrev_b32_e32 v5, 3, v41
	v_add_f32_e64 v19, |v62|, v19
	v_lshlrev_b32_e32 v1, 3, v1
	v_add3_u32 v204, 0, v3, v5
	v_ashrrev_i32_e32 v3, 4, v67
	v_add_u32_e32 v69, 0x2800, v38
	v_add3_u32 v176, 0, v1, v57
	v_add_f32_e64 v1, |v22|, v19
	v_lshlrev_b32_e32 v3, 3, v3
	v_lshlrev_b32_e32 v5, 3, v67
	v_add_f32_e64 v1, |v60|, v1
	v_add3_u32 v203, 0, v3, v5
	v_ashrrev_i32_e32 v3, 4, v69
	v_add_u32_e32 v73, 0x2a00, v38
	v_add_f32_e64 v1, |v20|, v1
	v_lshlrev_b32_e32 v3, 3, v3
	v_lshlrev_b32_e32 v5, 3, v69
	v_add_f32_e64 v1, |v58|, v1
	v_add3_u32 v202, 0, v3, v5
	v_ashrrev_i32_e32 v3, 4, v73
	v_add_u32_e32 v80, 0x2c00, v38
	v_add_f32_e64 v1, |v70|, v1
	v_lshlrev_b32_e32 v3, 3, v3
	v_lshlrev_b32_e32 v5, 3, v73
	s_waitcnt vmcnt(0)
	s_barrier
	ds_write_b64 v185, v[194:195]
	v_add_f32_e64 v1, |v56|, v1
	v_add3_u32 v194, 0, v3, v5
	v_ashrrev_i32_e32 v3, 4, v80
	v_add_u32_e32 v81, 0x2e00, v38
	v_add_f32_e64 v1, |v18|, v1
	v_lshlrev_b32_e32 v3, 3, v3
	v_lshlrev_b32_e32 v5, 3, v80
	v_add_f32_e64 v1, |v76|, v1
	v_add3_u32 v191, 0, v3, v5
	v_ashrrev_i32_e32 v3, 4, v81
	v_add_u32_e32 v82, 0x3000, v38
	v_add_f32_e64 v1, |v16|, v1
	v_lshlrev_b32_e32 v3, 3, v3
	v_lshlrev_b32_e32 v5, 3, v81
	v_add_f32_e64 v1, |v78|, v1
	v_add3_u32 v190, 0, v3, v5
	v_ashrrev_i32_e32 v3, 4, v82
	v_add_u32_e32 v83, 0x3200, v38
	v_add_f32_e64 v1, |v68|, v1
	v_lshlrev_b32_e32 v3, 3, v3
	v_lshlrev_b32_e32 v5, 3, v82
	v_add_f32_e64 v1, |v74|, v1
	v_add3_u32 v189, 0, v3, v5
	v_ashrrev_i32_e32 v3, 4, v83
	v_add_u32_e32 v84, 0x3400, v38
	v_add_f32_e64 v1, |v66|, v1
	v_lshlrev_b32_e32 v3, 3, v3
	v_lshlrev_b32_e32 v5, 3, v83
	v_add_f32_e64 v1, |v72|, v1
	v_add3_u32 v188, 0, v3, v5
	v_ashrrev_i32_e32 v3, 4, v84
	v_add_u32_e32 v85, 0x3600, v38
	v_add_f32_e64 v1, |v14|, v1
	v_lshlrev_b32_e32 v3, 3, v3
	v_lshlrev_b32_e32 v5, 3, v84
	v_add_f32_e64 v1, |v12|, v1
	v_add3_u32 v187, 0, v3, v5
	v_ashrrev_i32_e32 v3, 4, v85
	v_add_f32_e64 v1, |v10|, v1
	v_lshlrev_b32_e32 v3, 3, v3
	v_lshlrev_b32_e32 v5, 3, v85
	v_add_f32_e64 v1, |v8|, v1
	v_add3_u32 v186, 0, v3, v5
	v_and_b32_e32 v3, 64, v242
	v_add_f32_e64 v1, |v6|, v1
	v_add_u32_e32 v3, 64, v3
	v_xor_b32_e32 v5, 32, v242
	v_add_u32_e32 v40, 0x200, v38
	v_add_f32_e64 v1, |v4|, v1
	v_cmp_lt_i32_e32 vcc, v5, v3
	v_ashrrev_i32_e32 v21, 4, v40
	v_add_f32_e64 v1, |v0|, v1
	v_cndmask_b32_e32 v5, v242, v5, vcc
	v_lshlrev_b32_e32 v21, 3, v21
	v_add_f32_e64 v1, |v2|, v1
	v_lshlrev_b32_e32 v5, 2, v5
	v_add3_u32 v184, 0, v21, v57
	v_ashrrev_i32_e32 v21, 4, v36
	ds_bpermute_b32 v5, v5, v1
	v_lshlrev_b32_e32 v21, 3, v21
	v_add3_u32 v183, 0, v21, v57
	v_ashrrev_i32_e32 v21, 4, v34
	v_lshlrev_b32_e32 v21, 3, v21
	v_add3_u32 v182, 0, v21, v57
	v_ashrrev_i32_e32 v21, 4, v32
	v_lshlrev_b32_e32 v21, 3, v21
	s_waitcnt lgkmcnt(0)
	v_add_f32_e32 v1, v1, v5
	v_xor_b32_e32 v5, 16, v242
	v_add3_u32 v181, 0, v21, v57
	v_ashrrev_i32_e32 v21, 4, v30
	v_cmp_lt_i32_e32 vcc, v5, v3
	v_lshlrev_b32_e32 v21, 3, v21
	v_add3_u32 v180, 0, v21, v57
	v_cndmask_b32_e32 v5, v242, v5, vcc
	v_ashrrev_i32_e32 v21, 4, v28
	v_lshlrev_b32_e32 v5, 2, v5
	v_lshlrev_b32_e32 v21, 3, v21
	ds_bpermute_b32 v5, v5, v1
	v_add3_u32 v179, 0, v21, v57
	v_ashrrev_i32_e32 v21, 4, v26
	v_lshlrev_b32_e32 v21, 3, v21
	v_add3_u32 v178, 0, v21, v57
	v_ashrrev_i32_e32 v21, 4, v24
	v_add_u32_e32 v86, 0x3800, v38
	v_lshlrev_b32_e32 v21, 3, v21
	v_mov_b32_e32 v43, v195
	v_mov_b32_e32 v55, v195
	v_mov_b32_e32 v53, v195
	v_mov_b32_e32 v51, v195
	v_mov_b32_e32 v49, v195
	v_mov_b32_e32 v47, v195
	v_mov_b32_e32 v45, v195
	v_add3_u32 v177, 0, v21, v57
	v_mov_b32_e32 v65, v195
	v_mov_b32_e32 v63, v195
	v_mov_b32_e32 v23, v195
	v_mov_b32_e32 v61, v195
	v_mov_b32_e32 v21, v195
	v_mov_b32_e32 v59, v195
	v_mov_b32_e32 v71, v195
	v_mov_b32_e32 v57, v195
	v_mov_b32_e32 v19, v195
	v_mov_b32_e32 v77, v195
	v_mov_b32_e32 v17, v195
	v_mov_b32_e32 v79, v195
	v_mov_b32_e32 v69, v195
	v_mov_b32_e32 v75, v195
	v_mov_b32_e32 v67, v195
	v_mov_b32_e32 v73, v195
	v_mov_b32_e32 v15, v195
	v_mov_b32_e32 v13, v195
	v_mov_b32_e32 v11, v195
	v_mov_b32_e32 v9, v195
	v_ashrrev_i32_e32 v7, 4, v86
	s_waitcnt lgkmcnt(0)
	v_add_f32_e32 v1, v1, v5
	v_xor_b32_e32 v5, 8, v242
	ds_write_b64 v184, v[42:43] offset:4096
	ds_write_b64 v183, v[54:55] offset:8192
	ds_write_b64 v182, v[52:53] offset:12288
	ds_write_b64 v181, v[50:51] offset:16384
	ds_write_b64 v180, v[48:49] offset:20480
	ds_write_b64 v179, v[46:47] offset:24576
	ds_write_b64 v178, v[44:45] offset:28672
	ds_write_b64 v177, v[64:65] offset:32768
	ds_write_b64 v176, v[62:63] offset:36864
	ds_write_b64 v175, v[22:23] offset:40960
	ds_write_b64 v174, v[60:61] offset:45056
	ds_write_b64 v173, v[20:21] offset:49152
	ds_write_b64 v172, v[58:59] offset:53248
	ds_write_b64 v171, v[70:71] offset:57344
	ds_write_b64 v170, v[56:57] offset:61440
	ds_write_b64 v206, v[18:19]
	ds_write_b64 v205, v[76:77]
	ds_write_b64 v204, v[16:17]
	ds_write_b64 v203, v[78:79]
	ds_write_b64 v202, v[68:69]
	ds_write_b64 v194, v[74:75]
	ds_write_b64 v191, v[66:67]
	ds_write_b64 v190, v[72:73]
	ds_write_b64 v189, v[14:15]
	ds_write_b64 v188, v[12:13]
	ds_write_b64 v187, v[10:11]
	ds_write_b64 v186, v[8:9]
	v_lshlrev_b32_e32 v7, 3, v7
	v_lshlrev_b32_e32 v8, 3, v86
	v_cmp_lt_i32_e32 vcc, v5, v3
	v_add_u32_e32 v87, 0x3a00, v38
	v_add3_u32 v207, 0, v7, v8
	v_mov_b32_e32 v7, v195
	v_cndmask_b32_e32 v5, v242, v5, vcc
	ds_write_b64 v207, v[6:7]
	v_ashrrev_i32_e32 v6, 4, v87
	v_lshlrev_b32_e32 v5, 2, v5
	v_lshlrev_b32_e32 v6, 3, v6
	ds_bpermute_b32 v7, v5, v1
	v_lshlrev_b32_e32 v5, 3, v87
	v_add3_u32 v208, 0, v6, v5
	v_mov_b32_e32 v5, v195
	ds_write_b64 v208, v[4:5]
	v_xor_b32_e32 v4, 4, v242
	v_cmp_lt_i32_e32 vcc, v4, v3
	s_waitcnt lgkmcnt(1)
	v_add_f32_e32 v1, v1, v7
	v_add_u32_e32 v88, 0x3c00, v38
	v_cndmask_b32_e32 v4, v242, v4, vcc
	v_lshlrev_b32_e32 v4, 2, v4
	ds_bpermute_b32 v4, v4, v1
	v_ashrrev_i32_e32 v5, 4, v88
	v_lshlrev_b32_e32 v5, 3, v5
	v_lshlrev_b32_e32 v6, 3, v88
	v_add3_u32 v209, 0, v5, v6
	s_waitcnt lgkmcnt(0)
	v_add_f32_e32 v4, v1, v4
	v_xor_b32_e32 v1, 2, v242
	v_cmp_lt_i32_e32 vcc, v1, v3
	v_add_u32_e32 v89, 0x3e00, v38
	s_nop 0
	v_cndmask_b32_e32 v1, v242, v1, vcc
	v_lshlrev_b32_e32 v1, 2, v1
	ds_bpermute_b32 v5, v1, v4
	v_mov_b32_e32 v1, v195
	ds_write_b64 v209, v[0:1]
	v_xor_b32_e32 v1, 1, v242
	v_cmp_lt_i32_e32 vcc, v1, v3
	v_ashrrev_i32_e32 v0, 4, v89
	v_lshlrev_b32_e32 v6, 3, v0
	v_cndmask_b32_e32 v1, v242, v1, vcc
	s_waitcnt lgkmcnt(1)
	v_add_f32_e32 v0, v4, v5
	v_lshlrev_b32_e32 v1, 2, v1
	ds_bpermute_b32 v1, v1, v0
	v_lshlrev_b32_e32 v3, 3, v89
	v_add3_u32 v210, 0, v6, v3
	v_mov_b32_e32 v3, v195
	ds_write_b64 v210, v[2:3]
	s_and_saveexec_b64 s[2:3], s[40:41]
	s_cbranch_execz .LBB0_686
	s_waitcnt lgkmcnt(1)
	v_add_f32_e32 v0, v0, v1
	ds_write_b32 v169, v0
